# S5 scan passes A and B: next block's first u-row load goes straight into the carried registers instead of a scratch quad waited for at once (was one exposed memory round trip per 64-token block)
# speedup vs baseline: 1.0055x; 1.0005x over previous
; __device__ __forceinline__ int opq(int v) { asm volatile("" : "+v"(v)); return v; }
; __device__ __forceinline__ void ssm_stage_load(const Args& a, size_t row0, int ntok, int gq, u32x4 (&pre)[2]) {
;     const int tid = opq(threadIdx.x); const bf16_t* Z = (const bf16_t*)(a.ws + WS_C);
; #pragma unroll
;     for (int k = 0; k < 2; ++k) { const int idx = tid + 512 * k, t = idx >> 4, c8 = idx & 15; if (idx < ntok * 16) pre[k] = *(const u32x4*)(Z + (row0 + t) * INC + ZU + gq * 128 + c8 * 8); }
; }
; __global__ void __launch_bounds__(512, 2) mk_fwd(Args a) {
;     ...
;                 for (int blk = 0; blk < SEGB; ++blk) { u32x4 cur[2] = {pre[0], pre[1]};
;                     if (blk + 1 < SEGB) ssm_stage_load(a, r0 + (blk + 1) * SBLK, SBLK, gq, pre);
.LBB0_345:
	v_mov_b32_e32 v64, v184
	s_lshl_b32 s14, s23, 6
	s_add_u32 s14, s12, s14
	v_lshlrev_b32_e32 v0, 3, v64
	v_and_b32_e32 v0, 0x78, v0
	v_mov_b64_e32 v[4:5], v[20:21]
	s_addc_u32 s15, s13, 0
	v_cmp_gt_i32_e32 vcc, s80, v64
	v_lshlrev_b32_e32 v0, 1, v0
	v_mov_b64_e32 v[6:7], v[22:23]
	v_mov_b64_e32 v[8:9], v[24:25]
	v_mov_b64_e32 v[10:11], v[26:27]
	s_and_saveexec_b64 s[16:17], vcc
	s_cbranch_execz .LBB0_347
	v_ashrrev_i32_e32 v4, 4, v64
	v_ashrrev_i32_e32 v5, 31, v4
	v_lshl_add_u64 v[4:5], s[14:15], 0, v[4:5]
	v_mov_b64_e32 v[6:7], s[70:71]
	v_mad_u64_u32 v[6:7], s[24:25], v4, s87, v[6:7]
	v_mad_i32_i24 v7, v5, s87, v7
	s_lshl_b32 s26, s22, 1
	v_lshl_add_u64 v[4:5], v[6:7], 0, s[26:27]
	v_lshl_add_u64 v[4:5], v[4:5], 0, v[0:1]
	v_add_co_u32_e32 v4, vcc, 0x7b00000, v4
	s_nop 1
	v_addc_co_u32_e32 v5, vcc, 0, v5, vcc
	global_load_dwordx4 v[4:7], v[4:5], off offset:1536
	v_mov_b64_e32 v[8:9], v[24:25]
	v_mov_b64_e32 v[10:11], v[26:27]

; __device__ __forceinline__ int opq(int v) { asm volatile("" : "+v"(v)); return v; }
; __device__ __forceinline__ void ssm_stage_load(const Args& a, size_t row0, int ntok, int gq, u32x4 (&pre)[2]) {
;     const int tid = opq(threadIdx.x); const bf16_t* Z = (const bf16_t*)(a.ws + WS_C);
; #pragma unroll
;     for (int k = 0; k < 2; ++k) { const int idx = tid + 512 * k, t = idx >> 4, c8 = idx & 15; if (idx < ntok * 16) pre[k] = *(const u32x4*)(Z + (row0 + t) * INC + ZU + gq * 128 + c8 * 8); }
; }
; __global__ void __launch_bounds__(512, 2) mk_fwd(Args a) {
;     ...
;                 for (int blk = 0; blk < SEGB; ++blk) { u32x4 cur[2] = {pre[0], pre[1]};
;                     if (blk + 1 < SEGB) ssm_stage_load(a, r0 + (blk + 1) * SBLK, SBLK, gq, pre);
.LBB0_459:
	v_mov_b32_e32 v84, v184
	s_lshl_b32 s8, s12, 6
	s_add_u32 s8, s0, s8
	v_lshlrev_b32_e32 v0, 3, v84
	v_and_b32_e32 v0, 0x78, v0
	v_mov_b64_e32 v[26:27], v[18:19]
	s_addc_u32 s9, s1, 0
	v_cmp_gt_i32_e32 vcc, s80, v84
	v_lshlrev_b32_e32 v0, 1, v0
	v_mov_b64_e32 v[24:25], v[16:17]
	v_mov_b64_e32 v[22:23], v[14:15]
	v_mov_b64_e32 v[20:21], v[12:13]
	s_and_saveexec_b64 s[10:11], vcc
	s_cbranch_execz .LBB0_461
	v_ashrrev_i32_e32 v20, 4, v84
	v_ashrrev_i32_e32 v21, 31, v20
	v_lshl_add_u64 v[20:21], s[8:9], 0, v[20:21]
	v_mov_b64_e32 v[22:23], s[70:71]
	v_mad_u64_u32 v[22:23], s[14:15], v20, s87, v[22:23]
	v_mad_i32_i24 v23, v21, s87, v23
	s_lshl_b32 s26, s29, 1
	v_lshl_add_u64 v[20:21], v[22:23], 0, s[26:27]
	v_lshl_add_u64 v[20:21], v[20:21], 0, v[0:1]
	v_add_co_u32_e32 v20, vcc, 0x7b00000, v20
	s_nop 1
	v_addc_co_u32_e32 v21, vcc, 0, v21, vcc
	global_load_dwordx4 v[20:23], v[20:21], off offset:1536
	v_mov_b64_e32 v[26:27], v[18:19]
	v_mov_b64_e32 v[24:25], v[16:17]
